# G1 GEMMs via LDS-DMA (global_load_lds) BK=32 3-stage swizzled ring; OUT early-issue; cg sync replaced
# speedup vs baseline: 1.0156x; 1.0004x over previous
.LBB0_279:
	s_lshl_b32 s2, s9, 7
	s_or_b32 s3, s2, 32
	s_ashr_i32 s9, s3, 31
	s_ashr_i32 s11, s2, 31
	s_sub_u32 s10, s3, s2
	v_add_u32_e32 v2, s2, v181
	s_subb_u32 s11, s9, s11
	s_lshl_b32 s3, s8, 8
	v_ashrrev_i32_e32 v3, 31, v2
	v_add_u32_e32 v6, s3, v181
	v_lshlrev_b64 v[2:3], 11, v[2:3]
	v_ashrrev_i32_e32 v7, 31, v6
	v_lshl_add_u64 v[4:5], v[182:183], 0, v[2:3]
	v_lshlrev_b64 v[6:7], 11, v[6:7]
	s_lshl_b64 s[8:9], s[10:11], 11
	v_lshl_add_u64 v[8:9], v[184:185], 0, v[6:7]
	v_lshl_add_u64 v[10:11], v[4:5], 0, s[8:9]
	v_lshl_add_u64 v[12:13], v[10:11], 0, s[8:9]
	v_add_co_u32_e32 v4, vcc, s26, v8
	v_lshl_add_u64 v[10:11], v[12:13], 0, s[8:9]
	s_nop 0
	v_addc_co_u32_e32 v5, vcc, 0, v9, vcc
	v_add_co_u32_e32 v4, vcc, s78, v8
	v_lshl_add_u64 v[204:205], v[200:201], 0, v[2:3]
	s_nop 0
	v_addc_co_u32_e32 v5, vcc, 0, v9, vcc
	v_add_co_u32_e32 v10, vcc, s79, v8
	v_mov_b32_e32 v2, 0
	s_nop 0
	v_addc_co_u32_e32 v11, vcc, 0, v9, vcc
	v_add_co_u32_e32 v4, vcc, s0, v8
	v_lshl_add_u64 v[202:203], v[198:199], 0, v[6:7]
	s_nop 0
	v_addc_co_u32_e32 v5, vcc, 0, v9, vcc
	v_add_co_u32_e32 v10, vcc, s33, v8
	s_mov_b64 s[22:23], 0
	s_nop 0
	v_addc_co_u32_e32 v11, vcc, 0, v9, vcc
	v_add_co_u32_e32 v4, vcc, 0x60000, v8
	v_mov_b32_e32 v3, v2
	s_nop 0
	v_addc_co_u32_e32 v5, vcc, 0, v9, vcc
	v_add_co_u32_e32 v8, vcc, 0x70000, v8
	v_mov_b32_e32 v6, v2
	s_nop 0
	v_addc_co_u32_e32 v9, vcc, 0, v9, vcc
	v_mov_b32_e32 v4, v2
	v_mov_b32_e32 v5, v2
	v_mov_b32_e32 v7, v2
	v_mov_b32_e32 v8, v2
	v_mov_b32_e32 v9, v2
	v_mov_b32_e32 v10, v2
	v_mov_b32_e32 v11, v2
	v_mov_b32_e32 v12, v2
	v_mov_b32_e32 v13, v2
	v_mov_b32_e32 v14, v2
	v_mov_b32_e32 v15, v2
	v_mov_b32_e32 v16, v2
	v_mov_b32_e32 v17, v2
	v_mov_b32_e32 v18, v2
	v_mov_b32_e32 v19, v2
	v_mov_b32_e32 v20, v2
	v_mov_b32_e32 v21, v2
	v_mov_b32_e32 v22, v2
	v_mov_b32_e32 v23, v2
	v_mov_b32_e32 v24, v2
	v_mov_b32_e32 v25, v2
	v_mov_b32_e32 v26, v2
	v_mov_b32_e32 v27, v2
	v_mov_b32_e32 v28, v2
	v_mov_b32_e32 v29, v2
	v_mov_b32_e32 v30, v2
	v_mov_b32_e32 v31, v2
	v_mov_b32_e32 v32, v2
	v_mov_b32_e32 v33, v2
	v_mov_b32_e32 v34, v2
	v_mov_b32_e32 v35, v2
	v_mov_b32_e32 v36, v2
	v_mov_b32_e32 v37, v2
	v_mov_b32_e32 v38, v2
	v_mov_b32_e32 v39, v2
	v_mov_b32_e32 v40, v2
	v_mov_b32_e32 v41, v2
	v_mov_b32_e32 v42, v2
	v_mov_b32_e32 v43, v2
	v_mov_b32_e32 v44, v2
	v_mov_b32_e32 v45, v2
	v_mov_b32_e32 v46, v2
	v_mov_b32_e32 v47, v2
	v_mov_b32_e32 v48, v2
	v_mov_b32_e32 v49, v2
	v_mov_b32_e32 v50, v2
	v_mov_b32_e32 v51, v2
	v_mov_b32_e32 v52, v2
	v_mov_b32_e32 v53, v2
	v_mov_b32_e32 v54, v2
	v_mov_b32_e32 v55, v2
	v_mov_b32_e32 v56, v2
	v_mov_b32_e32 v57, v2
	v_mov_b32_e32 v58, v2
	v_mov_b32_e32 v59, v2
	v_mov_b32_e32 v60, v2
	v_mov_b32_e32 v61, v2
	v_mov_b32_e32 v62, v2
	v_mov_b32_e32 v63, v2
	v_mov_b32_e32 v64, v2
	v_mov_b32_e32 v65, v2
	v_mov_b32_e32 v66, v2
	v_mov_b32_e32 v67, v2
	v_mov_b32_e32 v68, v2
	v_mov_b32_e32 v69, v2
	v_mov_b32_e32 v70, v2
	v_mov_b32_e32 v71, v2
	v_mov_b32_e32 v72, v2
	v_mov_b32_e32 v73, v2
	v_mov_b32_e32 v74, v2
	v_mov_b32_e32 v75, v2
	v_mov_b32_e32 v76, v2
	v_mov_b32_e32 v77, v2
	v_mov_b32_e32 v78, v2
	v_mov_b32_e32 v79, v2
	v_mov_b32_e32 v80, v2
	v_mov_b32_e32 v81, v2
	v_mov_b32_e32 v82, v2
	v_mov_b32_e32 v83, v2
	v_mov_b32_e32 v84, v2
	v_mov_b32_e32 v85, v2
	v_mov_b32_e32 v86, v2
	v_mov_b32_e32 v87, v2
	v_mov_b32_e32 v88, v2
	v_mov_b32_e32 v89, v2
	v_mov_b32_e32 v90, v2
	v_mov_b32_e32 v91, v2
	v_mov_b32_e32 v92, v2
	v_mov_b32_e32 v93, v2
	v_mov_b32_e32 v94, v2
	v_mov_b32_e32 v95, v2
	v_mov_b32_e32 v96, v2
	v_mov_b32_e32 v97, v2
	v_mov_b32_e32 v98, v2
	v_mov_b32_e32 v99, v2
	v_mov_b32_e32 v100, v2
	v_mov_b32_e32 v101, v2
	v_mov_b32_e32 v102, v2
	v_mov_b32_e32 v103, v2
	v_mov_b32_e32 v104, v2
	v_mov_b32_e32 v105, v2
	v_mov_b32_e32 v106, v2
	v_mov_b32_e32 v107, v2
	v_mov_b32_e32 v108, v2
	v_mov_b32_e32 v109, v2
	v_mov_b32_e32 v110, v2
	v_mov_b32_e32 v111, v2
	v_mov_b32_e32 v112, v2
	v_mov_b32_e32 v113, v2
	v_mov_b32_e32 v114, v2
	v_mov_b32_e32 v115, v2
	v_mov_b32_e32 v116, v2
	v_mov_b32_e32 v117, v2
	v_mov_b32_e32 v118, v2
	v_mov_b32_e32 v119, v2
	v_mov_b32_e32 v120, v2
	v_mov_b32_e32 v121, v2
	v_mov_b32_e32 v122, v2
	v_mov_b32_e32 v123, v2
	v_mov_b32_e32 v124, v2
	v_mov_b32_e32 v125, v2
	v_mov_b32_e32 v126, v2
	v_mov_b32_e32 v127, v2
	v_mov_b32_e32 v128, v2
	v_mov_b32_e32 v129, v2
.LBB0_280:
	v_and_b32_e32 v130, 63, v206
	v_lshrrev_b32_e32 v131, 6, v206
	v_and_b32_e32 v132, 7, v206
	v_readfirstlane_b32 s23, v131
	v_lshlrev_b32_e32 v132, 4, v132
	v_lshrrev_b32_e32 v133, 3, v206
	v_lshl_add_u32 v132, v133, 11, v132
	v_lshrrev_b32_e32 v133, 4, v130
	v_xor_b32_e32 v133, v133, v130
	v_and_b32_e32 v133, 3, v133
	v_lshlrev_b32_e32 v133, 4, v133
	v_lshrrev_b32_e32 v134, 2, v130
	v_lshl_add_u32 v133, v134, 11, v133
	v_sub_u32_e32 v133, v133, v132
	v_mov_b32_e32 v135, 0
	v_lshl_add_u32 v134, v131, 16, v133
	v_add_u32_e32 v134, 0xd400000, v134
	v_lshl_add_u64 v[232:233], v[204:205], 0, v[134:135]
	v_add_u32_e32 v134, 0x8000, v134
	v_lshl_add_u64 v[234:235], v[204:205], 0, v[134:135]
	v_lshl_add_u32 v134, v131, 17, v133
	v_add_u32_e32 v134, 0xac00000, v134
	v_lshl_add_u64 v[236:237], v[202:203], 0, v[134:135]
	v_add_u32_e32 v134, 0x8000, v134
	v_lshl_add_u64 v[238:239], v[202:203], 0, v[134:135]
	v_add_u32_e32 v134, 0x8000, v134
	v_lshl_add_u64 v[240:241], v[202:203], 0, v[134:135]
	v_add_u32_e32 v134, 0x8000, v134
	v_lshl_add_u64 v[244:245], v[202:203], 0, v[134:135]
	v_and_b32_e32 v136, 31, v130
	v_lshrrev_b32_e32 v137, 5, v130
	v_bfe_u32 v138, v130, 2, 2
	v_xor_b32_e32 v137, v137, v138
	v_lshlrev_b32_e32 v137, 4, v137
	v_lshrrev_b32_e32 v139, 1, v131
	v_lshl_add_u32 v139, v139, 6, v136
	v_lshl_add_u32 v246, v139, 6, v137
	v_xor_b32_e32 v247, 32, v246
	v_and_b32_e32 v139, 1, v131
	v_lshl_add_u32 v139, v139, 7, v136
	v_lshl_add_u32 v248, v139, 6, v137
	v_add_u32_e32 v248, 0x2000, v248
	v_xor_b32_e32 v249, 32, v248
	s_lshl_b32 s8, s23, 11
	s_lshl_b32 s9, s23, 12
	s_add_u32 s9, s9, 0x2000
	s_waitcnt lgkmcnt(0)
	s_barrier
	s_add_u32 m0, s8, 0x0
	s_nop 0
	global_load_lds_dwordx4 v[232:233], off
	v_lshl_add_u64 v[232:233], v[232:233], 0, 64
	s_add_u32 m0, s8, 0x400
	s_nop 0
	global_load_lds_dwordx4 v[234:235], off
	v_lshl_add_u64 v[234:235], v[234:235], 0, 64
	s_add_u32 m0, s9, 0x0
	s_nop 0
	global_load_lds_dwordx4 v[236:237], off
	v_lshl_add_u64 v[236:237], v[236:237], 0, 64
	s_add_u32 m0, s9, 0x400
	s_nop 0
	global_load_lds_dwordx4 v[238:239], off
	v_lshl_add_u64 v[238:239], v[238:239], 0, 64
	s_add_u32 m0, s9, 0x800
	s_nop 0
	global_load_lds_dwordx4 v[240:241], off
	v_lshl_add_u64 v[240:241], v[240:241], 0, 64
	s_add_u32 m0, s9, 0xc00
	s_nop 0
	global_load_lds_dwordx4 v[244:245], off
	v_lshl_add_u64 v[244:245], v[244:245], 0, 64
	s_add_u32 m0, s8, 0x6000
	s_nop 0
	global_load_lds_dwordx4 v[232:233], off
	v_lshl_add_u64 v[232:233], v[232:233], 0, 64
	s_add_u32 m0, s8, 0x6400
	s_nop 0
	global_load_lds_dwordx4 v[234:235], off
	v_lshl_add_u64 v[234:235], v[234:235], 0, 64
	s_add_u32 m0, s9, 0x6000
	s_nop 0
	global_load_lds_dwordx4 v[236:237], off
	v_lshl_add_u64 v[236:237], v[236:237], 0, 64
	s_add_u32 m0, s9, 0x6400
	s_nop 0
	global_load_lds_dwordx4 v[238:239], off
	v_lshl_add_u64 v[238:239], v[238:239], 0, 64
	s_add_u32 m0, s9, 0x6800
	s_nop 0
	global_load_lds_dwordx4 v[240:241], off
	v_lshl_add_u64 v[240:241], v[240:241], 0, 64
	s_add_u32 m0, s9, 0x6c00
	s_nop 0
	global_load_lds_dwordx4 v[244:245], off
	v_lshl_add_u64 v[244:245], v[244:245], 0, 64
	s_mov_b32 s22, 0
.Ldma_loop_g1o:
	s_waitcnt vmcnt(6)
	s_barrier
	ds_read_b128 v[130:133], v246
	ds_read_b128 v[146:149], v248
	ds_read_b128 v[134:137], v246 offset:2048
	ds_read_b128 v[150:153], v248 offset:2048
	ds_read_b128 v[154:157], v248 offset:4096
	ds_read_b128 v[158:161], v248 offset:6144
	ds_read_b128 v[138:141], v247
	ds_read_b128 v[162:165], v249
	ds_read_b128 v[142:145], v247 offset:2048
	ds_read_b128 v[166:169], v249 offset:2048
	ds_read_b128 v[170:173], v249 offset:4096
	ds_read_b128 v[174:177], v249 offset:6144
	s_waitcnt lgkmcnt(10)
	v_mfma_f32_32x32x16_bf16 v[114:129], v[146:149], v[130:133], v[114:129]
	s_add_u32 m0, s8, 0xd900
	s_nop 0
	global_load_lds_dwordx4 v[232:233], off
	v_lshl_add_u64 v[232:233], v[232:233], 0, 64
	s_waitcnt lgkmcnt(9)
	v_mfma_f32_32x32x16_bf16 v[82:97], v[146:149], v[134:137], v[82:97]
	s_add_u32 m0, s8, 0xdd00
	s_nop 0
	global_load_lds_dwordx4 v[234:235], off
	v_lshl_add_u64 v[234:235], v[234:235], 0, 64
	s_waitcnt lgkmcnt(8)
	v_mfma_f32_32x32x16_bf16 v[98:113], v[150:153], v[130:133], v[98:113]
	s_add_u32 m0, s9, 0xd900
	s_nop 0
	global_load_lds_dwordx4 v[236:237], off
	v_lshl_add_u64 v[236:237], v[236:237], 0, 64
	v_mfma_f32_32x32x16_bf16 v[66:81], v[150:153], v[134:137], v[66:81]
	s_add_u32 m0, s9, 0xdd00
	s_nop 0
	global_load_lds_dwordx4 v[238:239], off
	v_lshl_add_u64 v[238:239], v[238:239], 0, 64
	s_waitcnt lgkmcnt(7)
	v_mfma_f32_32x32x16_bf16 v[50:65], v[154:157], v[130:133], v[50:65]
	s_add_u32 m0, s9, 0xe100
	s_nop 0
	global_load_lds_dwordx4 v[240:241], off
	v_lshl_add_u64 v[240:241], v[240:241], 0, 64
	v_mfma_f32_32x32x16_bf16 v[18:33], v[154:157], v[134:137], v[18:33]
	s_add_u32 m0, s9, 0xe500
	s_nop 0
	global_load_lds_dwordx4 v[244:245], off
	v_lshl_add_u64 v[244:245], v[244:245], 0, 64
	s_waitcnt lgkmcnt(6)
	v_mfma_f32_32x32x16_bf16 v[34:49], v[158:161], v[130:133], v[34:49]
	v_mfma_f32_32x32x16_bf16 v[2:17], v[158:161], v[134:137], v[2:17]
	s_waitcnt lgkmcnt(4)
	v_mfma_f32_32x32x16_bf16 v[114:129], v[162:165], v[138:141], v[114:129]
	s_waitcnt lgkmcnt(3)
	v_mfma_f32_32x32x16_bf16 v[82:97], v[162:165], v[142:145], v[82:97]
	s_waitcnt lgkmcnt(2)
	v_mfma_f32_32x32x16_bf16 v[98:113], v[166:169], v[138:141], v[98:113]
	v_mfma_f32_32x32x16_bf16 v[66:81], v[166:169], v[142:145], v[66:81]
	s_waitcnt lgkmcnt(1)
	v_mfma_f32_32x32x16_bf16 v[50:65], v[170:173], v[138:141], v[50:65]
	v_mfma_f32_32x32x16_bf16 v[18:33], v[170:173], v[142:145], v[18:33]
	s_waitcnt lgkmcnt(0)
	v_mfma_f32_32x32x16_bf16 v[34:49], v[174:177], v[138:141], v[34:49]
	v_mfma_f32_32x32x16_bf16 v[2:17], v[174:177], v[142:145], v[2:17]
	s_waitcnt vmcnt(6)
	s_barrier
	ds_read_b128 v[130:133], v246 offset:24576
	ds_read_b128 v[146:149], v248 offset:24576
	ds_read_b128 v[134:137], v246 offset:26624
	ds_read_b128 v[150:153], v248 offset:26624
	ds_read_b128 v[154:157], v248 offset:28672
	ds_read_b128 v[158:161], v248 offset:30720
	ds_read_b128 v[138:141], v247 offset:24576
	ds_read_b128 v[162:165], v249 offset:24576
	ds_read_b128 v[142:145], v247 offset:26624
	ds_read_b128 v[166:169], v249 offset:26624
	ds_read_b128 v[170:173], v249 offset:28672
	ds_read_b128 v[174:177], v249 offset:30720
	s_waitcnt lgkmcnt(10)
	v_mfma_f32_32x32x16_bf16 v[114:129], v[146:149], v[130:133], v[114:129]
	s_add_u32 m0, s8, 0x0
	s_nop 0
	global_load_lds_dwordx4 v[232:233], off
	v_lshl_add_u64 v[232:233], v[232:233], 0, 64
	s_waitcnt lgkmcnt(9)
	v_mfma_f32_32x32x16_bf16 v[82:97], v[146:149], v[134:137], v[82:97]
	s_add_u32 m0, s8, 0x400
	s_nop 0
	global_load_lds_dwordx4 v[234:235], off
	v_lshl_add_u64 v[234:235], v[234:235], 0, 64
	s_waitcnt lgkmcnt(8)
	v_mfma_f32_32x32x16_bf16 v[98:113], v[150:153], v[130:133], v[98:113]
	s_add_u32 m0, s9, 0x0
	s_nop 0
	global_load_lds_dwordx4 v[236:237], off
	v_lshl_add_u64 v[236:237], v[236:237], 0, 64
	v_mfma_f32_32x32x16_bf16 v[66:81], v[150:153], v[134:137], v[66:81]
	s_add_u32 m0, s9, 0x400
	s_nop 0
	global_load_lds_dwordx4 v[238:239], off
	v_lshl_add_u64 v[238:239], v[238:239], 0, 64
	s_waitcnt lgkmcnt(7)
	v_mfma_f32_32x32x16_bf16 v[50:65], v[154:157], v[130:133], v[50:65]
	s_add_u32 m0, s9, 0x800
	s_nop 0
	global_load_lds_dwordx4 v[240:241], off
	v_lshl_add_u64 v[240:241], v[240:241], 0, 64
	v_mfma_f32_32x32x16_bf16 v[18:33], v[154:157], v[134:137], v[18:33]
	s_add_u32 m0, s9, 0xc00
	s_nop 0
	global_load_lds_dwordx4 v[244:245], off
	v_lshl_add_u64 v[244:245], v[244:245], 0, 64
	s_waitcnt lgkmcnt(6)
	v_mfma_f32_32x32x16_bf16 v[34:49], v[158:161], v[130:133], v[34:49]
	v_mfma_f32_32x32x16_bf16 v[2:17], v[158:161], v[134:137], v[2:17]
	s_waitcnt lgkmcnt(4)
	v_mfma_f32_32x32x16_bf16 v[114:129], v[162:165], v[138:141], v[114:129]
	s_waitcnt lgkmcnt(3)
	v_mfma_f32_32x32x16_bf16 v[82:97], v[162:165], v[142:145], v[82:97]
	s_waitcnt lgkmcnt(2)
	v_mfma_f32_32x32x16_bf16 v[98:113], v[166:169], v[138:141], v[98:113]
	v_mfma_f32_32x32x16_bf16 v[66:81], v[166:169], v[142:145], v[66:81]
	s_waitcnt lgkmcnt(1)
	v_mfma_f32_32x32x16_bf16 v[50:65], v[170:173], v[138:141], v[50:65]
	v_mfma_f32_32x32x16_bf16 v[18:33], v[170:173], v[142:145], v[18:33]
	s_waitcnt lgkmcnt(0)
	v_mfma_f32_32x32x16_bf16 v[34:49], v[174:177], v[138:141], v[34:49]
	v_mfma_f32_32x32x16_bf16 v[2:17], v[174:177], v[142:145], v[2:17]
	s_waitcnt vmcnt(6)
	s_barrier
	ds_read_b128 v[130:133], v246 offset:55552
	ds_read_b128 v[146:149], v248 offset:55552
	ds_read_b128 v[134:137], v246 offset:57600
	ds_read_b128 v[150:153], v248 offset:57600
	ds_read_b128 v[154:157], v248 offset:59648
	ds_read_b128 v[158:161], v248 offset:61696
	ds_read_b128 v[138:141], v247 offset:55552
	ds_read_b128 v[162:165], v249 offset:55552
	ds_read_b128 v[142:145], v247 offset:57600
	ds_read_b128 v[166:169], v249 offset:57600
	ds_read_b128 v[170:173], v249 offset:59648
	ds_read_b128 v[174:177], v249 offset:61696
	s_waitcnt lgkmcnt(10)
	v_mfma_f32_32x32x16_bf16 v[114:129], v[146:149], v[130:133], v[114:129]
	s_add_u32 m0, s8, 0x6000
	s_nop 0
	global_load_lds_dwordx4 v[232:233], off
	v_lshl_add_u64 v[232:233], v[232:233], 0, 64
	s_waitcnt lgkmcnt(9)
	v_mfma_f32_32x32x16_bf16 v[82:97], v[146:149], v[134:137], v[82:97]
	s_add_u32 m0, s8, 0x6400
	s_nop 0
	global_load_lds_dwordx4 v[234:235], off
	v_lshl_add_u64 v[234:235], v[234:235], 0, 64
	s_waitcnt lgkmcnt(8)
	v_mfma_f32_32x32x16_bf16 v[98:113], v[150:153], v[130:133], v[98:113]
	s_add_u32 m0, s9, 0x6000
	s_nop 0
	global_load_lds_dwordx4 v[236:237], off
	v_lshl_add_u64 v[236:237], v[236:237], 0, 64
	v_mfma_f32_32x32x16_bf16 v[66:81], v[150:153], v[134:137], v[66:81]
	s_add_u32 m0, s9, 0x6400
	s_nop 0
	global_load_lds_dwordx4 v[238:239], off
	v_lshl_add_u64 v[238:239], v[238:239], 0, 64
	s_waitcnt lgkmcnt(7)
	v_mfma_f32_32x32x16_bf16 v[50:65], v[154:157], v[130:133], v[50:65]
	s_add_u32 m0, s9, 0x6800
	s_nop 0
	global_load_lds_dwordx4 v[240:241], off
	v_lshl_add_u64 v[240:241], v[240:241], 0, 64
	v_mfma_f32_32x32x16_bf16 v[18:33], v[154:157], v[134:137], v[18:33]
	s_add_u32 m0, s9, 0x6c00
	s_nop 0
	global_load_lds_dwordx4 v[244:245], off
	v_lshl_add_u64 v[244:245], v[244:245], 0, 64
	s_waitcnt lgkmcnt(6)
	v_mfma_f32_32x32x16_bf16 v[34:49], v[158:161], v[130:133], v[34:49]
	v_mfma_f32_32x32x16_bf16 v[2:17], v[158:161], v[134:137], v[2:17]
	s_waitcnt lgkmcnt(4)
	v_mfma_f32_32x32x16_bf16 v[114:129], v[162:165], v[138:141], v[114:129]
	s_waitcnt lgkmcnt(3)
	v_mfma_f32_32x32x16_bf16 v[82:97], v[162:165], v[142:145], v[82:97]
	s_waitcnt lgkmcnt(2)
	v_mfma_f32_32x32x16_bf16 v[98:113], v[166:169], v[138:141], v[98:113]
	v_mfma_f32_32x32x16_bf16 v[66:81], v[166:169], v[142:145], v[66:81]
	s_waitcnt lgkmcnt(1)
	v_mfma_f32_32x32x16_bf16 v[50:65], v[170:173], v[138:141], v[50:65]
	v_mfma_f32_32x32x16_bf16 v[18:33], v[170:173], v[142:145], v[18:33]
	s_waitcnt lgkmcnt(0)
	v_mfma_f32_32x32x16_bf16 v[34:49], v[174:177], v[138:141], v[34:49]
	v_mfma_f32_32x32x16_bf16 v[2:17], v[174:177], v[142:145], v[2:17]
	s_add_u32 s22, s22, 1
	s_cmp_lt_u32 s22, 10
	s_cbranch_scc1 .Ldma_loop_g1o
	s_waitcnt vmcnt(6)
	s_barrier
	ds_read_b128 v[130:133], v246
	ds_read_b128 v[146:149], v248
	ds_read_b128 v[134:137], v246 offset:2048
	ds_read_b128 v[150:153], v248 offset:2048
	ds_read_b128 v[154:157], v248 offset:4096
	ds_read_b128 v[158:161], v248 offset:6144
	ds_read_b128 v[138:141], v247
	ds_read_b128 v[162:165], v249
	ds_read_b128 v[142:145], v247 offset:2048
	ds_read_b128 v[166:169], v249 offset:2048
	ds_read_b128 v[170:173], v249 offset:4096
	ds_read_b128 v[174:177], v249 offset:6144
	s_waitcnt lgkmcnt(10)
	v_mfma_f32_32x32x16_bf16 v[114:129], v[146:149], v[130:133], v[114:129]
	s_waitcnt lgkmcnt(9)
	v_mfma_f32_32x32x16_bf16 v[82:97], v[146:149], v[134:137], v[82:97]
	s_waitcnt lgkmcnt(8)
	v_mfma_f32_32x32x16_bf16 v[98:113], v[150:153], v[130:133], v[98:113]
	v_mfma_f32_32x32x16_bf16 v[66:81], v[150:153], v[134:137], v[66:81]
	s_waitcnt lgkmcnt(7)
	v_mfma_f32_32x32x16_bf16 v[50:65], v[154:157], v[130:133], v[50:65]
	v_mfma_f32_32x32x16_bf16 v[18:33], v[154:157], v[134:137], v[18:33]
	s_waitcnt lgkmcnt(6)
	v_mfma_f32_32x32x16_bf16 v[34:49], v[158:161], v[130:133], v[34:49]
	v_mfma_f32_32x32x16_bf16 v[2:17], v[158:161], v[134:137], v[2:17]
	s_waitcnt lgkmcnt(4)
	v_mfma_f32_32x32x16_bf16 v[114:129], v[162:165], v[138:141], v[114:129]
	s_waitcnt lgkmcnt(3)
	v_mfma_f32_32x32x16_bf16 v[82:97], v[162:165], v[142:145], v[82:97]
	s_waitcnt lgkmcnt(2)
	v_mfma_f32_32x32x16_bf16 v[98:113], v[166:169], v[138:141], v[98:113]
	v_mfma_f32_32x32x16_bf16 v[66:81], v[166:169], v[142:145], v[66:81]
	s_waitcnt lgkmcnt(1)
	v_mfma_f32_32x32x16_bf16 v[50:65], v[170:173], v[138:141], v[50:65]
	v_mfma_f32_32x32x16_bf16 v[18:33], v[170:173], v[142:145], v[18:33]
	s_waitcnt lgkmcnt(0)
	v_mfma_f32_32x32x16_bf16 v[34:49], v[174:177], v[138:141], v[34:49]
	v_mfma_f32_32x32x16_bf16 v[2:17], v[174:177], v[142:145], v[2:17]
	s_waitcnt vmcnt(0)
	s_barrier
	ds_read_b128 v[130:133], v246 offset:24576
	ds_read_b128 v[146:149], v248 offset:24576
	ds_read_b128 v[134:137], v246 offset:26624
	ds_read_b128 v[150:153], v248 offset:26624
	ds_read_b128 v[154:157], v248 offset:28672
	ds_read_b128 v[158:161], v248 offset:30720
	ds_read_b128 v[138:141], v247 offset:24576
	ds_read_b128 v[162:165], v249 offset:24576
	ds_read_b128 v[142:145], v247 offset:26624
	ds_read_b128 v[166:169], v249 offset:26624
	ds_read_b128 v[170:173], v249 offset:28672
	ds_read_b128 v[174:177], v249 offset:30720
	s_waitcnt lgkmcnt(10)
	v_mfma_f32_32x32x16_bf16 v[114:129], v[146:149], v[130:133], v[114:129]
	s_waitcnt lgkmcnt(9)
	v_mfma_f32_32x32x16_bf16 v[82:97], v[146:149], v[134:137], v[82:97]
	s_waitcnt lgkmcnt(8)
	v_mfma_f32_32x32x16_bf16 v[98:113], v[150:153], v[130:133], v[98:113]
	v_mfma_f32_32x32x16_bf16 v[66:81], v[150:153], v[134:137], v[66:81]
	s_waitcnt lgkmcnt(7)
	v_mfma_f32_32x32x16_bf16 v[50:65], v[154:157], v[130:133], v[50:65]
	v_mfma_f32_32x32x16_bf16 v[18:33], v[154:157], v[134:137], v[18:33]
	s_waitcnt lgkmcnt(6)
	v_mfma_f32_32x32x16_bf16 v[34:49], v[158:161], v[130:133], v[34:49]
	v_mfma_f32_32x32x16_bf16 v[2:17], v[158:161], v[134:137], v[2:17]
	s_waitcnt lgkmcnt(4)
	v_mfma_f32_32x32x16_bf16 v[114:129], v[162:165], v[138:141], v[114:129]
	s_waitcnt lgkmcnt(3)
	v_mfma_f32_32x32x16_bf16 v[82:97], v[162:165], v[142:145], v[82:97]
	s_waitcnt lgkmcnt(2)
	v_mfma_f32_32x32x16_bf16 v[98:113], v[166:169], v[138:141], v[98:113]
	v_mfma_f32_32x32x16_bf16 v[66:81], v[166:169], v[142:145], v[66:81]
	s_waitcnt lgkmcnt(1)
	v_mfma_f32_32x32x16_bf16 v[50:65], v[170:173], v[138:141], v[50:65]
	v_mfma_f32_32x32x16_bf16 v[18:33], v[170:173], v[142:145], v[18:33]
	s_waitcnt lgkmcnt(0)
	v_mfma_f32_32x32x16_bf16 v[34:49], v[174:177], v[138:141], v[34:49]
	v_mfma_f32_32x32x16_bf16 v[2:17], v[174:177], v[142:145], v[2:17]
	s_barrier
	v_add_u32_e32 v136, s2, v187
	v_ashrrev_i32_e32 v134, 11, v136
	v_and_b32_e32 v157, 0x7c0, v136
	v_or_b32_e32 v138, s3, v191
	v_ashrrev_i32_e32 v139, 31, v138
	v_ashrrev_i32_e32 v159, 6, v138
	v_or_b32_e32 v132, v136, v189
	v_ashrrev_i32_e32 v133, 31, v132
	v_lshl_add_u64 v[142:143], v[132:133], 2, s[40:41]
	global_load_dword v132, v[142:143], off
	v_lshlrev_b32_e32 v130, 12, v134
	v_ashrrev_i32_e32 v131, 31, v130
	v_lshl_add_u64 v[130:131], v[130:131], 2, s[42:43]
	v_lshl_add_u64 v[130:131], v[138:139], 2, v[130:131]
	v_lshl_add_u64 v[140:141], v[130:131], 0, v[0:1]
	s_waitcnt vmcnt(0)
	v_fmamk_f32 v132, v132, 0x3a800000, v208
	v_cmp_gt_f32_e32 vcc, s84, v132
	v_mul_f32_e32 v133, 0x4b800000, v132
	s_nop 0
	v_cndmask_b32_e32 v132, v132, v133, vcc
	v_rsq_f32_e32 v132, v132
	s_nop 0
	v_mul_f32_e32 v133, 0x45800000, v132
	v_cndmask_b32_e32 v156, v132, v133, vcc
	global_load_dword v132, v[142:143], off offset:128
	s_waitcnt vmcnt(0)
	v_fmamk_f32 v132, v132, 0x3a800000, v208
	v_cmp_gt_f32_e32 vcc, s84, v132
	v_mul_f32_e32 v133, 0x4b800000, v132
	s_nop 0
	v_cndmask_b32_e32 v132, v132, v133, vcc
	v_rsq_f32_e32 v132, v132
	s_nop 0
	v_mul_f32_e32 v133, 0x45800000, v132
	v_cndmask_b32_e32 v158, v132, v133, vcc
	global_load_dwordx4 v[150:153], v[140:141], off
	global_load_dwordx4 v[160:163], v[140:141], off offset:32
	global_load_dwordx4 v[164:167], v[140:141], off offset:64
	global_load_dwordx4 v[130:133], v[140:141], off offset:96
	global_load_dwordx4 v[168:171], v[140:141], off offset:128
	v_cmp_lt_i32_e32 vcc, 31, v159
	s_waitcnt vmcnt(4)
	v_pk_fma_f32 v[148:149], v[114:115], v[156:157], v[150:151] op_sel_hi:[1,0,1]
	v_pk_fma_f32 v[114:115], v[82:83], v[158:159], v[150:151] op_sel_hi:[1,0,1]
	v_pk_fma_f32 v[150:151], v[116:117], v[156:157], v[152:153] op_sel_hi:[1,0,1]
	v_pk_fma_f32 v[116:117], v[84:85], v[158:159], v[152:153] op_sel_hi:[1,0,1]
	s_waitcnt vmcnt(0)
	v_pk_fma_f32 v[144:145], v[98:99], v[156:157], v[168:169] op_sel_hi:[1,0,1]
	v_pk_fma_f32 v[98:99], v[66:67], v[158:159], v[168:169] op_sel_hi:[1,0,1]
	v_pk_fma_f32 v[146:147], v[100:101], v[156:157], v[170:171] op_sel_hi:[1,0,1]
	v_pk_fma_f32 v[100:101], v[68:69], v[158:159], v[170:171] op_sel_hi:[1,0,1]
	global_load_dwordx4 v[66:69], v[140:141], off offset:160
	v_pk_fma_f32 v[152:153], v[118:119], v[156:157], v[160:161] op_sel_hi:[1,0,1]
	v_pk_fma_f32 v[154:155], v[120:121], v[156:157], v[162:163] op_sel_hi:[1,0,1]
	v_pk_fma_f32 v[122:123], v[122:123], v[156:157], v[164:165] op_sel_hi:[1,0,1]
	v_pk_fma_f32 v[124:125], v[124:125], v[156:157], v[166:167] op_sel_hi:[1,0,1]
	v_pk_fma_f32 v[126:127], v[126:127], v[156:157], v[130:131] op_sel_hi:[1,0,1]
	v_pk_fma_f32 v[84:85], v[94:95], v[158:159], v[130:131] op_sel_hi:[1,0,1]
	v_pk_fma_f32 v[128:129], v[128:129], v[156:157], v[132:133] op_sel_hi:[1,0,1]
	s_waitcnt vmcnt(0)
	v_pk_fma_f32 v[118:119], v[102:103], v[156:157], v[66:67] op_sel_hi:[1,0,1]
	v_pk_fma_f32 v[70:71], v[70:71], v[158:159], v[66:67] op_sel_hi:[1,0,1]
	v_pk_fma_f32 v[120:121], v[104:105], v[156:157], v[68:69] op_sel_hi:[1,0,1]
	v_pk_fma_f32 v[72:73], v[72:73], v[158:159], v[68:69] op_sel_hi:[1,0,1]
	global_load_dwordx4 v[66:69], v[140:141], off offset:192
	v_pk_fma_f32 v[102:103], v[86:87], v[158:159], v[160:161] op_sel_hi:[1,0,1]
	v_pk_fma_f32 v[104:105], v[88:89], v[158:159], v[162:163] op_sel_hi:[1,0,1]
	v_pk_fma_f32 v[88:89], v[90:91], v[158:159], v[164:165] op_sel_hi:[1,0,1]
	v_pk_fma_f32 v[90:91], v[92:93], v[158:159], v[166:167] op_sel_hi:[1,0,1]
	v_pk_fma_f32 v[86:87], v[96:97], v[158:159], v[132:133] op_sel_hi:[1,0,1]
	s_waitcnt vmcnt(0)
	v_pk_fma_f32 v[106:107], v[106:107], v[156:157], v[66:67] op_sel_hi:[1,0,1]
	v_pk_fma_f32 v[66:67], v[74:75], v[158:159], v[66:67] op_sel_hi:[1,0,1]
	v_pk_fma_f32 v[108:109], v[108:109], v[156:157], v[68:69] op_sel_hi:[1,0,1]
	v_pk_fma_f32 v[68:69], v[76:77], v[158:159], v[68:69] op_sel_hi:[1,0,1]
	global_load_dwordx4 v[74:77], v[140:141], off offset:224
	s_waitcnt vmcnt(0)
	v_pk_fma_f32 v[110:111], v[110:111], v[156:157], v[74:75] op_sel_hi:[1,0,1]
	v_pk_fma_f32 v[82:83], v[78:79], v[158:159], v[74:75] op_sel_hi:[1,0,1]
	v_pk_fma_f32 v[94:95], v[112:113], v[156:157], v[76:77] op_sel_hi:[1,0,1]
	v_pk_fma_f32 v[80:81], v[80:81], v[158:159], v[76:77] op_sel_hi:[1,0,1]
	s_and_saveexec_b64 s[2:3], vcc
	s_xor_b64 s[2:3], exec, s[2:3]
	s_cbranch_execz .LBB0_287
	v_cmp_lt_u32_e32 vcc, 47, v159
	v_cvt_pk_bf16_f32 v74, v152, s0
	v_cvt_pk_bf16_f32 v75, v153, s0
	v_cvt_pk_bf16_f32 v76, v154, s0
	v_cvt_pk_bf16_f32 v77, v155, s0
	s_and_saveexec_b64 s[8:9], vcc
	s_xor_b64 s[22:23], exec, s[8:9]
	s_cbranch_execz .LBB0_284
	s_mov_b32 s8, 0x5040100
	v_cvt_pk_bf16_f32 v93, v150, v151
	v_cvt_pk_bf16_f32 v92, v148, v149
	v_perm_b32 v77, v77, v76, s8
	v_perm_b32 v76, v75, v74, s8
	ds_write2_b64 v226, v[92:93], v[76:77] offset1:2
	v_cvt_pk_bf16_f32 v75, v124, v125
	v_cvt_pk_bf16_f32 v74, v122, v123
	v_cvt_pk_bf16_f32 v77, v128, v129
	v_cvt_pk_bf16_f32 v76, v126, v127
	ds_write2_b64 v226, v[74:75], v[76:77] offset0:4 offset1:6
	v_cvt_pk_bf16_f32 v75, v146, v147
	v_cvt_pk_bf16_f32 v74, v144, v145
	v_cvt_pk_bf16_f32 v77, v120, v121
	v_cvt_pk_bf16_f32 v76, v118, v119
	ds_write2_b64 v226, v[74:75], v[76:77] offset0:8 offset1:10
	v_cvt_pk_bf16_f32 v75, v108, v109
	v_cvt_pk_bf16_f32 v74, v106, v107
	v_cvt_pk_bf16_f32 v77, v94, v95
	v_cvt_pk_bf16_f32 v76, v110, v111
	v_ashrrev_i32_e32 v137, 31, v136
	ds_write2_b64 v226, v[74:75], v[76:77] offset0:12 offset1:14
	v_cvt_pk_bf16_f32 v75, v116, v117
	v_cvt_pk_bf16_f32 v74, v114, v115
	v_cvt_pk_bf16_f32 v77, v104, v105
	v_cvt_pk_bf16_f32 v76, v102, v103
	v_add_u32_e32 v92, 0x1000, v226
	v_lshlrev_b64 v[78:79], 11, v[136:137]
	ds_write2_b64 v92, v[74:75], v[76:77] offset0:64 offset1:66
	v_cvt_pk_bf16_f32 v75, v90, v91
	v_cvt_pk_bf16_f32 v74, v88, v89
	v_cvt_pk_bf16_f32 v77, v86, v87
	v_cvt_pk_bf16_f32 v76, v84, v85
	v_lshl_add_u64 v[78:79], s[38:39], 0, v[78:79]
	v_mov_b32_e32 v139, v1
	ds_write2_b64 v92, v[74:75], v[76:77] offset0:68 offset1:70
	v_cvt_pk_bf16_f32 v75, v100, v101
	v_cvt_pk_bf16_f32 v74, v98, v99
	v_cvt_pk_bf16_f32 v73, v72, v73
	v_cvt_pk_bf16_f32 v72, v70, v71
	v_cvt_pk_bf16_f32 v69, v68, v69
	v_cvt_pk_bf16_f32 v68, v66, v67
	v_cvt_pk_bf16_f32 v67, v80, v81
	v_cvt_pk_bf16_f32 v66, v82, v83
	v_lshl_add_u64 v[78:79], v[138:139], 1, v[78:79]
	ds_write2_b64 v92, v[74:75], v[72:73] offset0:72 offset1:74
	ds_write2_b64 v92, v[68:69], v[66:67] offset0:76 offset1:78
	v_lshlrev_b32_e32 v66, 1, v188
	v_mov_b32_e32 v67, v1
	v_lshl_add_u64 v[66:67], v[78:79], 0, v[66:67]
	v_lshlrev_b32_e32 v68, 1, v180
	v_mov_b32_e32 v69, v1
	v_lshl_add_u64 v[74:75], v[66:67], 0, v[68:69]
	ds_read_b128 v[66:69], v227
	ds_read_b128 v[70:73], v227 offset:1152
	s_mov_b32 s8, 0x7ffe000
	v_add_co_u32_e32 v76, vcc, s8, v74
	s_mov_b32 s8, 0x8002000
	s_nop 0
	v_addc_co_u32_e32 v77, vcc, 0, v75, vcc
	s_waitcnt lgkmcnt(1)
	global_store_dwordx4 v[76:77], v[66:69], off offset:2048
	s_nop 1
	v_add_co_u32_e32 v66, vcc, s8, v74
	s_mov_b32 s8, 0x8006000
	s_nop 0
	v_addc_co_u32_e32 v67, vcc, 0, v75, vcc
	s_waitcnt lgkmcnt(0)
	global_store_dwordx4 v[66:67], v[70:73], off offset:2048
	ds_read_b128 v[66:69], v227 offset:2304
	ds_read_b128 v[70:73], v227 offset:3456
	v_add_co_u32_e32 v76, vcc, s8, v74
	s_mov_b32 s8, 0x800a000
	s_nop 0
	v_addc_co_u32_e32 v77, vcc, 0, v75, vcc
	s_waitcnt lgkmcnt(1)
	global_store_dwordx4 v[76:77], v[66:69], off offset:2048
	s_nop 1
	v_add_co_u32_e32 v66, vcc, s8, v74
	s_mov_b32 s8, 0x800e000
	s_nop 0
	v_addc_co_u32_e32 v67, vcc, 0, v75, vcc
	s_waitcnt lgkmcnt(0)
	global_store_dwordx4 v[66:67], v[70:73], off offset:2048
	ds_read_b128 v[66:69], v227 offset:4608
	ds_read_b128 v[70:73], v227 offset:5760
	v_add_co_u32_e32 v76, vcc, s8, v74
	s_nop 1
	v_addc_co_u32_e32 v77, vcc, 0, v75, vcc
	s_waitcnt lgkmcnt(1)
	global_store_dwordx4 v[76:77], v[66:69], off offset:2048
	s_nop 1
	v_add_co_u32_e32 v66, vcc, 0x8012000, v74
	s_nop 1
	v_addc_co_u32_e32 v67, vcc, 0, v75, vcc
	s_waitcnt lgkmcnt(0)
	global_store_dwordx4 v[66:67], v[70:73], off offset:2048
	ds_read_b128 v[66:69], v227 offset:6912
	ds_read_b128 v[70:73], v227 offset:8064
	v_add_co_u32_e32 v76, vcc, 0x8016000, v74
	s_nop 1
	v_addc_co_u32_e32 v77, vcc, 0, v75, vcc
	s_waitcnt lgkmcnt(1)
	global_store_dwordx4 v[76:77], v[66:69], off offset:2048
	s_nop 1
	v_add_co_u32_e32 v66, vcc, 0x801a000, v74
	s_nop 1
	v_addc_co_u32_e32 v67, vcc, 0, v75, vcc
	s_waitcnt lgkmcnt(0)
	global_store_dwordx4 v[66:67], v[70:73], off offset:2048

.LBB0_313:
	s_lshl_b32 s2, s7, 7
	s_or_b32 s3, s2, 32
	s_ashr_i32 s7, s3, 31
	s_ashr_i32 s9, s2, 31
	s_sub_u32 s8, s3, s2
	v_add_u32_e32 v2, s2, v181
	s_subb_u32 s9, s7, s9
	s_lshl_b32 s3, s6, 8
	v_ashrrev_i32_e32 v3, 31, v2
	v_add_u32_e32 v6, s3, v181
	v_lshlrev_b64 v[2:3], 11, v[2:3]
	v_ashrrev_i32_e32 v7, 31, v6
	v_lshl_add_u64 v[4:5], v[182:183], 0, v[2:3]
	v_lshlrev_b64 v[6:7], 11, v[6:7]
	s_lshl_b64 s[6:7], s[8:9], 11
	v_lshl_add_u64 v[8:9], v[184:185], 0, v[6:7]
	v_lshl_add_u64 v[10:11], v[4:5], 0, s[6:7]
	v_lshl_add_u64 v[12:13], v[10:11], 0, s[6:7]
	v_add_co_u32_e32 v4, vcc, s26, v8
	v_lshl_add_u64 v[10:11], v[12:13], 0, s[6:7]
	s_nop 0
	v_addc_co_u32_e32 v5, vcc, 0, v9, vcc
	v_add_co_u32_e32 v4, vcc, s78, v8
	v_lshl_add_u64 v[202:203], v[198:199], 0, v[2:3]
	s_nop 0
	v_addc_co_u32_e32 v5, vcc, 0, v9, vcc
	v_add_co_u32_e32 v10, vcc, s79, v8
	v_mov_b32_e32 v2, 0
	s_nop 0
	v_addc_co_u32_e32 v11, vcc, 0, v9, vcc
	v_add_co_u32_e32 v4, vcc, s0, v8
	v_lshl_add_u64 v[200:201], v[196:197], 0, v[6:7]
	s_nop 0
	v_addc_co_u32_e32 v5, vcc, 0, v9, vcc
	v_add_co_u32_e32 v10, vcc, s33, v8
	s_mov_b64 s[22:23], 0
	s_nop 0
	v_addc_co_u32_e32 v11, vcc, 0, v9, vcc
	v_add_co_u32_e32 v4, vcc, 0x60000, v8
	v_mov_b32_e32 v3, v2
	s_nop 0
	v_addc_co_u32_e32 v5, vcc, 0, v9, vcc
	v_add_co_u32_e32 v8, vcc, 0x70000, v8
	v_mov_b32_e32 v6, v2
	s_nop 0
	v_addc_co_u32_e32 v9, vcc, 0, v9, vcc
	v_mov_b32_e32 v4, v2
	v_mov_b32_e32 v5, v2
	v_mov_b32_e32 v7, v2
	v_mov_b32_e32 v8, v2
	v_mov_b32_e32 v9, v2
	v_mov_b32_e32 v10, v2
	v_mov_b32_e32 v11, v2
	v_mov_b32_e32 v12, v2
	v_mov_b32_e32 v13, v2
	v_mov_b32_e32 v14, v2
	v_mov_b32_e32 v15, v2
	v_mov_b32_e32 v16, v2
	v_mov_b32_e32 v17, v2
	v_mov_b32_e32 v34, v2
	v_mov_b32_e32 v35, v2
	v_mov_b32_e32 v36, v2
	v_mov_b32_e32 v37, v2
	v_mov_b32_e32 v38, v2
	v_mov_b32_e32 v39, v2
	v_mov_b32_e32 v40, v2
	v_mov_b32_e32 v41, v2
	v_mov_b32_e32 v42, v2
	v_mov_b32_e32 v43, v2
	v_mov_b32_e32 v44, v2
	v_mov_b32_e32 v45, v2
	v_mov_b32_e32 v46, v2
	v_mov_b32_e32 v47, v2
	v_mov_b32_e32 v48, v2
	v_mov_b32_e32 v49, v2
	v_mov_b32_e32 v18, v2
	v_mov_b32_e32 v19, v2
	v_mov_b32_e32 v20, v2
	v_mov_b32_e32 v21, v2
	v_mov_b32_e32 v22, v2
	v_mov_b32_e32 v23, v2
	v_mov_b32_e32 v24, v2
	v_mov_b32_e32 v25, v2
	v_mov_b32_e32 v26, v2
	v_mov_b32_e32 v27, v2
	v_mov_b32_e32 v28, v2
	v_mov_b32_e32 v29, v2
	v_mov_b32_e32 v30, v2
	v_mov_b32_e32 v31, v2
	v_mov_b32_e32 v32, v2
	v_mov_b32_e32 v33, v2
	v_mov_b32_e32 v50, v2
	v_mov_b32_e32 v51, v2
	v_mov_b32_e32 v52, v2
	v_mov_b32_e32 v53, v2
	v_mov_b32_e32 v54, v2
	v_mov_b32_e32 v55, v2
	v_mov_b32_e32 v56, v2
	v_mov_b32_e32 v57, v2
	v_mov_b32_e32 v58, v2
	v_mov_b32_e32 v59, v2
	v_mov_b32_e32 v60, v2
	v_mov_b32_e32 v61, v2
	v_mov_b32_e32 v62, v2
	v_mov_b32_e32 v63, v2
	v_mov_b32_e32 v64, v2
	v_mov_b32_e32 v65, v2
	v_mov_b32_e32 v66, v2
	v_mov_b32_e32 v67, v2
	v_mov_b32_e32 v68, v2
	v_mov_b32_e32 v69, v2
	v_mov_b32_e32 v70, v2
	v_mov_b32_e32 v71, v2
	v_mov_b32_e32 v72, v2
	v_mov_b32_e32 v73, v2
	v_mov_b32_e32 v74, v2
	v_mov_b32_e32 v75, v2
	v_mov_b32_e32 v76, v2
	v_mov_b32_e32 v77, v2
	v_mov_b32_e32 v78, v2
	v_mov_b32_e32 v79, v2
	v_mov_b32_e32 v80, v2
	v_mov_b32_e32 v81, v2
	v_mov_b32_e32 v98, v2
	v_mov_b32_e32 v99, v2
	v_mov_b32_e32 v100, v2
	v_mov_b32_e32 v101, v2
	v_mov_b32_e32 v102, v2
	v_mov_b32_e32 v103, v2
	v_mov_b32_e32 v104, v2
	v_mov_b32_e32 v105, v2
	v_mov_b32_e32 v106, v2
	v_mov_b32_e32 v107, v2
	v_mov_b32_e32 v108, v2
	v_mov_b32_e32 v109, v2
	v_mov_b32_e32 v110, v2
	v_mov_b32_e32 v111, v2
	v_mov_b32_e32 v112, v2
	v_mov_b32_e32 v113, v2
	v_mov_b32_e32 v82, v2
	v_mov_b32_e32 v83, v2
	v_mov_b32_e32 v84, v2
	v_mov_b32_e32 v85, v2
	v_mov_b32_e32 v86, v2
	v_mov_b32_e32 v87, v2
	v_mov_b32_e32 v88, v2
	v_mov_b32_e32 v89, v2
	v_mov_b32_e32 v90, v2
	v_mov_b32_e32 v91, v2
	v_mov_b32_e32 v92, v2
	v_mov_b32_e32 v93, v2
	v_mov_b32_e32 v94, v2
	v_mov_b32_e32 v95, v2
	v_mov_b32_e32 v96, v2
	v_mov_b32_e32 v97, v2
	v_mov_b32_e32 v114, v2
	v_mov_b32_e32 v115, v2
	v_mov_b32_e32 v116, v2
	v_mov_b32_e32 v117, v2
	v_mov_b32_e32 v118, v2
	v_mov_b32_e32 v119, v2
	v_mov_b32_e32 v120, v2
	v_mov_b32_e32 v121, v2
	v_mov_b32_e32 v122, v2
	v_mov_b32_e32 v123, v2
	v_mov_b32_e32 v124, v2
	v_mov_b32_e32 v125, v2
	v_mov_b32_e32 v126, v2
	v_mov_b32_e32 v127, v2
	v_mov_b32_e32 v128, v2
	v_mov_b32_e32 v129, v2
.LBB0_314:
	v_and_b32_e32 v130, 63, v206
	v_lshrrev_b32_e32 v131, 6, v206
	v_and_b32_e32 v132, 7, v206
	v_readfirstlane_b32 s23, v131
	v_lshlrev_b32_e32 v132, 4, v132
	v_lshrrev_b32_e32 v133, 3, v206
	v_lshl_add_u32 v132, v133, 11, v132
	v_lshrrev_b32_e32 v133, 4, v130
	v_xor_b32_e32 v133, v133, v130
	v_and_b32_e32 v133, 3, v133
	v_lshlrev_b32_e32 v133, 4, v133
	v_lshrrev_b32_e32 v134, 2, v130
	v_lshl_add_u32 v133, v134, 11, v133
	v_sub_u32_e32 v133, v133, v132
	v_mov_b32_e32 v135, 0
	v_lshl_add_u32 v134, v131, 16, v133
	v_add_u32_e32 v134, 0xd400000, v134
	v_lshl_add_u64 v[232:233], v[202:203], 0, v[134:135]
	v_add_u32_e32 v134, 0x8000, v134
	v_lshl_add_u64 v[234:235], v[202:203], 0, v[134:135]
	v_lshl_add_u32 v134, v131, 17, v133
	v_add_u32_e32 v134, 0xa000000, v134
	v_lshl_add_u64 v[236:237], v[200:201], 0, v[134:135]
	v_add_u32_e32 v134, 0x8000, v134
	v_lshl_add_u64 v[238:239], v[200:201], 0, v[134:135]
	v_add_u32_e32 v134, 0x8000, v134
	v_lshl_add_u64 v[240:241], v[200:201], 0, v[134:135]
	v_add_u32_e32 v134, 0x8000, v134
	v_lshl_add_u64 v[244:245], v[200:201], 0, v[134:135]
	v_and_b32_e32 v136, 31, v130
	v_lshrrev_b32_e32 v137, 5, v130
	v_bfe_u32 v138, v130, 2, 2
	v_xor_b32_e32 v137, v137, v138
	v_lshlrev_b32_e32 v137, 4, v137
	v_lshrrev_b32_e32 v139, 1, v131
	v_lshl_add_u32 v139, v139, 6, v136
	v_lshl_add_u32 v246, v139, 6, v137
	v_xor_b32_e32 v247, 32, v246
	v_and_b32_e32 v139, 1, v131
	v_lshl_add_u32 v139, v139, 7, v136
	v_lshl_add_u32 v248, v139, 6, v137
	v_add_u32_e32 v248, 0x2000, v248
	v_xor_b32_e32 v249, 32, v248
	s_lshl_b32 s6, s23, 11
	s_lshl_b32 s7, s23, 12
	s_add_u32 s7, s7, 0x2000
	s_waitcnt lgkmcnt(0)
	s_barrier
	s_add_u32 m0, s6, 0x0
	s_nop 0
	global_load_lds_dwordx4 v[232:233], off
	v_lshl_add_u64 v[232:233], v[232:233], 0, 64
	s_add_u32 m0, s6, 0x400
	s_nop 0
	global_load_lds_dwordx4 v[234:235], off
	v_lshl_add_u64 v[234:235], v[234:235], 0, 64
	s_add_u32 m0, s7, 0x0
	s_nop 0
	global_load_lds_dwordx4 v[236:237], off
	v_lshl_add_u64 v[236:237], v[236:237], 0, 64
	s_add_u32 m0, s7, 0x400
	s_nop 0
	global_load_lds_dwordx4 v[238:239], off
	v_lshl_add_u64 v[238:239], v[238:239], 0, 64
	s_add_u32 m0, s7, 0x800
	s_nop 0
	global_load_lds_dwordx4 v[240:241], off
	v_lshl_add_u64 v[240:241], v[240:241], 0, 64
	s_add_u32 m0, s7, 0xc00
	s_nop 0
	global_load_lds_dwordx4 v[244:245], off
	v_lshl_add_u64 v[244:245], v[244:245], 0, 64
	s_add_u32 m0, s6, 0x6000
	s_nop 0
	global_load_lds_dwordx4 v[232:233], off
	v_lshl_add_u64 v[232:233], v[232:233], 0, 64
	s_add_u32 m0, s6, 0x6400
	s_nop 0
	global_load_lds_dwordx4 v[234:235], off
	v_lshl_add_u64 v[234:235], v[234:235], 0, 64
	s_add_u32 m0, s7, 0x6000
	s_nop 0
	global_load_lds_dwordx4 v[236:237], off
	v_lshl_add_u64 v[236:237], v[236:237], 0, 64
	s_add_u32 m0, s7, 0x6400
	s_nop 0
	global_load_lds_dwordx4 v[238:239], off
	v_lshl_add_u64 v[238:239], v[238:239], 0, 64
	s_add_u32 m0, s7, 0x6800
	s_nop 0
	global_load_lds_dwordx4 v[240:241], off
	v_lshl_add_u64 v[240:241], v[240:241], 0, 64
	s_add_u32 m0, s7, 0x6c00
	s_nop 0
	global_load_lds_dwordx4 v[244:245], off
	v_lshl_add_u64 v[244:245], v[244:245], 0, 64
	s_mov_b32 s22, 0
.Ldma_loop_g1e:
	s_waitcnt vmcnt(6)
	s_barrier
	ds_read_b128 v[130:133], v246
	ds_read_b128 v[146:149], v248
	ds_read_b128 v[134:137], v246 offset:2048
	ds_read_b128 v[150:153], v248 offset:2048
	ds_read_b128 v[154:157], v248 offset:4096
	ds_read_b128 v[158:161], v248 offset:6144
	ds_read_b128 v[138:141], v247
	ds_read_b128 v[162:165], v249
	ds_read_b128 v[142:145], v247 offset:2048
	ds_read_b128 v[166:169], v249 offset:2048
	ds_read_b128 v[170:173], v249 offset:4096
	ds_read_b128 v[174:177], v249 offset:6144
	s_waitcnt lgkmcnt(10)
	v_mfma_f32_32x32x16_bf16 v[114:129], v[146:149], v[130:133], v[114:129]
	s_add_u32 m0, s6, 0xd900
	s_nop 0
	global_load_lds_dwordx4 v[232:233], off
	v_lshl_add_u64 v[232:233], v[232:233], 0, 64
	s_waitcnt lgkmcnt(9)
	v_mfma_f32_32x32x16_bf16 v[98:113], v[146:149], v[134:137], v[98:113]
	s_add_u32 m0, s6, 0xdd00
	s_nop 0
	global_load_lds_dwordx4 v[234:235], off
	v_lshl_add_u64 v[234:235], v[234:235], 0, 64
	s_waitcnt lgkmcnt(8)
	v_mfma_f32_32x32x16_bf16 v[82:97], v[150:153], v[130:133], v[82:97]
	s_add_u32 m0, s7, 0xd900
	s_nop 0
	global_load_lds_dwordx4 v[236:237], off
	v_lshl_add_u64 v[236:237], v[236:237], 0, 64
	v_mfma_f32_32x32x16_bf16 v[66:81], v[150:153], v[134:137], v[66:81]
	s_add_u32 m0, s7, 0xdd00
	s_nop 0
	global_load_lds_dwordx4 v[238:239], off
	v_lshl_add_u64 v[238:239], v[238:239], 0, 64
	s_waitcnt lgkmcnt(7)
	v_mfma_f32_32x32x16_bf16 v[50:65], v[154:157], v[130:133], v[50:65]
	s_add_u32 m0, s7, 0xe100
	s_nop 0
	global_load_lds_dwordx4 v[240:241], off
	v_lshl_add_u64 v[240:241], v[240:241], 0, 64
	v_mfma_f32_32x32x16_bf16 v[34:49], v[154:157], v[134:137], v[34:49]
	s_add_u32 m0, s7, 0xe500
	s_nop 0
	global_load_lds_dwordx4 v[244:245], off
	v_lshl_add_u64 v[244:245], v[244:245], 0, 64
	s_waitcnt lgkmcnt(6)
	v_mfma_f32_32x32x16_bf16 v[18:33], v[158:161], v[130:133], v[18:33]
	v_mfma_f32_32x32x16_bf16 v[2:17], v[158:161], v[134:137], v[2:17]
	s_waitcnt lgkmcnt(4)
	v_mfma_f32_32x32x16_bf16 v[114:129], v[162:165], v[138:141], v[114:129]
	s_waitcnt lgkmcnt(3)
	v_mfma_f32_32x32x16_bf16 v[98:113], v[162:165], v[142:145], v[98:113]
	s_waitcnt lgkmcnt(2)
	v_mfma_f32_32x32x16_bf16 v[82:97], v[166:169], v[138:141], v[82:97]
	v_mfma_f32_32x32x16_bf16 v[66:81], v[166:169], v[142:145], v[66:81]
	s_waitcnt lgkmcnt(1)
	v_mfma_f32_32x32x16_bf16 v[50:65], v[170:173], v[138:141], v[50:65]
	v_mfma_f32_32x32x16_bf16 v[34:49], v[170:173], v[142:145], v[34:49]
	s_waitcnt lgkmcnt(0)
	v_mfma_f32_32x32x16_bf16 v[18:33], v[174:177], v[138:141], v[18:33]
	v_mfma_f32_32x32x16_bf16 v[2:17], v[174:177], v[142:145], v[2:17]
	s_waitcnt vmcnt(6)
	s_barrier
	ds_read_b128 v[130:133], v246 offset:24576
	ds_read_b128 v[146:149], v248 offset:24576
	ds_read_b128 v[134:137], v246 offset:26624
	ds_read_b128 v[150:153], v248 offset:26624
	ds_read_b128 v[154:157], v248 offset:28672
	ds_read_b128 v[158:161], v248 offset:30720
	ds_read_b128 v[138:141], v247 offset:24576
	ds_read_b128 v[162:165], v249 offset:24576
	ds_read_b128 v[142:145], v247 offset:26624
	ds_read_b128 v[166:169], v249 offset:26624
	ds_read_b128 v[170:173], v249 offset:28672
	ds_read_b128 v[174:177], v249 offset:30720
	s_waitcnt lgkmcnt(10)
	v_mfma_f32_32x32x16_bf16 v[114:129], v[146:149], v[130:133], v[114:129]
	s_add_u32 m0, s6, 0x0
	s_nop 0
	global_load_lds_dwordx4 v[232:233], off
	v_lshl_add_u64 v[232:233], v[232:233], 0, 64
	s_waitcnt lgkmcnt(9)
	v_mfma_f32_32x32x16_bf16 v[98:113], v[146:149], v[134:137], v[98:113]
	s_add_u32 m0, s6, 0x400
	s_nop 0
	global_load_lds_dwordx4 v[234:235], off
	v_lshl_add_u64 v[234:235], v[234:235], 0, 64
	s_waitcnt lgkmcnt(8)
	v_mfma_f32_32x32x16_bf16 v[82:97], v[150:153], v[130:133], v[82:97]
	s_add_u32 m0, s7, 0x0
	s_nop 0
	global_load_lds_dwordx4 v[236:237], off
	v_lshl_add_u64 v[236:237], v[236:237], 0, 64
	v_mfma_f32_32x32x16_bf16 v[66:81], v[150:153], v[134:137], v[66:81]
	s_add_u32 m0, s7, 0x400
	s_nop 0
	global_load_lds_dwordx4 v[238:239], off
	v_lshl_add_u64 v[238:239], v[238:239], 0, 64
	s_waitcnt lgkmcnt(7)
	v_mfma_f32_32x32x16_bf16 v[50:65], v[154:157], v[130:133], v[50:65]
	s_add_u32 m0, s7, 0x800
	s_nop 0
	global_load_lds_dwordx4 v[240:241], off
	v_lshl_add_u64 v[240:241], v[240:241], 0, 64
	v_mfma_f32_32x32x16_bf16 v[34:49], v[154:157], v[134:137], v[34:49]
	s_add_u32 m0, s7, 0xc00
	s_nop 0
	global_load_lds_dwordx4 v[244:245], off
	v_lshl_add_u64 v[244:245], v[244:245], 0, 64
	s_waitcnt lgkmcnt(6)
	v_mfma_f32_32x32x16_bf16 v[18:33], v[158:161], v[130:133], v[18:33]
	v_mfma_f32_32x32x16_bf16 v[2:17], v[158:161], v[134:137], v[2:17]
	s_waitcnt lgkmcnt(4)
	v_mfma_f32_32x32x16_bf16 v[114:129], v[162:165], v[138:141], v[114:129]
	s_waitcnt lgkmcnt(3)
	v_mfma_f32_32x32x16_bf16 v[98:113], v[162:165], v[142:145], v[98:113]
	s_waitcnt lgkmcnt(2)
	v_mfma_f32_32x32x16_bf16 v[82:97], v[166:169], v[138:141], v[82:97]
	v_mfma_f32_32x32x16_bf16 v[66:81], v[166:169], v[142:145], v[66:81]
	s_waitcnt lgkmcnt(1)
	v_mfma_f32_32x32x16_bf16 v[50:65], v[170:173], v[138:141], v[50:65]
	v_mfma_f32_32x32x16_bf16 v[34:49], v[170:173], v[142:145], v[34:49]
	s_waitcnt lgkmcnt(0)
	v_mfma_f32_32x32x16_bf16 v[18:33], v[174:177], v[138:141], v[18:33]
	v_mfma_f32_32x32x16_bf16 v[2:17], v[174:177], v[142:145], v[2:17]
	s_waitcnt vmcnt(6)
	s_barrier
	ds_read_b128 v[130:133], v246 offset:55552
	ds_read_b128 v[146:149], v248 offset:55552
	ds_read_b128 v[134:137], v246 offset:57600
	ds_read_b128 v[150:153], v248 offset:57600
	ds_read_b128 v[154:157], v248 offset:59648
	ds_read_b128 v[158:161], v248 offset:61696
	ds_read_b128 v[138:141], v247 offset:55552
	ds_read_b128 v[162:165], v249 offset:55552
	ds_read_b128 v[142:145], v247 offset:57600
	ds_read_b128 v[166:169], v249 offset:57600
	ds_read_b128 v[170:173], v249 offset:59648
	ds_read_b128 v[174:177], v249 offset:61696
	s_waitcnt lgkmcnt(10)
	v_mfma_f32_32x32x16_bf16 v[114:129], v[146:149], v[130:133], v[114:129]
	s_add_u32 m0, s6, 0x6000
	s_nop 0
	global_load_lds_dwordx4 v[232:233], off
	v_lshl_add_u64 v[232:233], v[232:233], 0, 64
	s_waitcnt lgkmcnt(9)
	v_mfma_f32_32x32x16_bf16 v[98:113], v[146:149], v[134:137], v[98:113]
	s_add_u32 m0, s6, 0x6400
	s_nop 0
	global_load_lds_dwordx4 v[234:235], off
	v_lshl_add_u64 v[234:235], v[234:235], 0, 64
	s_waitcnt lgkmcnt(8)
	v_mfma_f32_32x32x16_bf16 v[82:97], v[150:153], v[130:133], v[82:97]
	s_add_u32 m0, s7, 0x6000
	s_nop 0
	global_load_lds_dwordx4 v[236:237], off
	v_lshl_add_u64 v[236:237], v[236:237], 0, 64
	v_mfma_f32_32x32x16_bf16 v[66:81], v[150:153], v[134:137], v[66:81]
	s_add_u32 m0, s7, 0x6400
	s_nop 0
	global_load_lds_dwordx4 v[238:239], off
	v_lshl_add_u64 v[238:239], v[238:239], 0, 64
	s_waitcnt lgkmcnt(7)
	v_mfma_f32_32x32x16_bf16 v[50:65], v[154:157], v[130:133], v[50:65]
	s_add_u32 m0, s7, 0x6800
	s_nop 0
	global_load_lds_dwordx4 v[240:241], off
	v_lshl_add_u64 v[240:241], v[240:241], 0, 64
	v_mfma_f32_32x32x16_bf16 v[34:49], v[154:157], v[134:137], v[34:49]
	s_add_u32 m0, s7, 0x6c00
	s_nop 0
	global_load_lds_dwordx4 v[244:245], off
	v_lshl_add_u64 v[244:245], v[244:245], 0, 64
	s_waitcnt lgkmcnt(6)
	v_mfma_f32_32x32x16_bf16 v[18:33], v[158:161], v[130:133], v[18:33]
	v_mfma_f32_32x32x16_bf16 v[2:17], v[158:161], v[134:137], v[2:17]
	s_waitcnt lgkmcnt(4)
	v_mfma_f32_32x32x16_bf16 v[114:129], v[162:165], v[138:141], v[114:129]
	s_waitcnt lgkmcnt(3)
	v_mfma_f32_32x32x16_bf16 v[98:113], v[162:165], v[142:145], v[98:113]
	s_waitcnt lgkmcnt(2)
	v_mfma_f32_32x32x16_bf16 v[82:97], v[166:169], v[138:141], v[82:97]
	v_mfma_f32_32x32x16_bf16 v[66:81], v[166:169], v[142:145], v[66:81]
	s_waitcnt lgkmcnt(1)
	v_mfma_f32_32x32x16_bf16 v[50:65], v[170:173], v[138:141], v[50:65]
	v_mfma_f32_32x32x16_bf16 v[34:49], v[170:173], v[142:145], v[34:49]
	s_waitcnt lgkmcnt(0)
	v_mfma_f32_32x32x16_bf16 v[18:33], v[174:177], v[138:141], v[18:33]
	v_mfma_f32_32x32x16_bf16 v[2:17], v[174:177], v[142:145], v[2:17]
	s_add_u32 s22, s22, 1
	s_cmp_lt_u32 s22, 10
	s_cbranch_scc1 .Ldma_loop_g1e
	s_waitcnt vmcnt(6)
	s_barrier
	ds_read_b128 v[130:133], v246
	ds_read_b128 v[146:149], v248
	ds_read_b128 v[134:137], v246 offset:2048
	ds_read_b128 v[150:153], v248 offset:2048
	ds_read_b128 v[154:157], v248 offset:4096
	ds_read_b128 v[158:161], v248 offset:6144
	ds_read_b128 v[138:141], v247
	ds_read_b128 v[162:165], v249
	ds_read_b128 v[142:145], v247 offset:2048
	ds_read_b128 v[166:169], v249 offset:2048
	ds_read_b128 v[170:173], v249 offset:4096
	ds_read_b128 v[174:177], v249 offset:6144
	s_waitcnt lgkmcnt(10)
	v_mfma_f32_32x32x16_bf16 v[114:129], v[146:149], v[130:133], v[114:129]
	s_waitcnt lgkmcnt(9)
	v_mfma_f32_32x32x16_bf16 v[98:113], v[146:149], v[134:137], v[98:113]
	s_waitcnt lgkmcnt(8)
	v_mfma_f32_32x32x16_bf16 v[82:97], v[150:153], v[130:133], v[82:97]
	v_mfma_f32_32x32x16_bf16 v[66:81], v[150:153], v[134:137], v[66:81]
	s_waitcnt lgkmcnt(7)
	v_mfma_f32_32x32x16_bf16 v[50:65], v[154:157], v[130:133], v[50:65]
	v_mfma_f32_32x32x16_bf16 v[34:49], v[154:157], v[134:137], v[34:49]
	s_waitcnt lgkmcnt(6)
	v_mfma_f32_32x32x16_bf16 v[18:33], v[158:161], v[130:133], v[18:33]
	v_mfma_f32_32x32x16_bf16 v[2:17], v[158:161], v[134:137], v[2:17]
	s_waitcnt lgkmcnt(4)
	v_mfma_f32_32x32x16_bf16 v[114:129], v[162:165], v[138:141], v[114:129]
	s_waitcnt lgkmcnt(3)
	v_mfma_f32_32x32x16_bf16 v[98:113], v[162:165], v[142:145], v[98:113]
	s_waitcnt lgkmcnt(2)
	v_mfma_f32_32x32x16_bf16 v[82:97], v[166:169], v[138:141], v[82:97]
	v_mfma_f32_32x32x16_bf16 v[66:81], v[166:169], v[142:145], v[66:81]
	s_waitcnt lgkmcnt(1)
	v_mfma_f32_32x32x16_bf16 v[50:65], v[170:173], v[138:141], v[50:65]
	v_mfma_f32_32x32x16_bf16 v[34:49], v[170:173], v[142:145], v[34:49]
	s_waitcnt lgkmcnt(0)
	v_mfma_f32_32x32x16_bf16 v[18:33], v[174:177], v[138:141], v[18:33]
	v_mfma_f32_32x32x16_bf16 v[2:17], v[174:177], v[142:145], v[2:17]
	s_waitcnt vmcnt(0)
	s_barrier
	ds_read_b128 v[130:133], v246 offset:24576
	ds_read_b128 v[146:149], v248 offset:24576
	ds_read_b128 v[134:137], v246 offset:26624
	ds_read_b128 v[150:153], v248 offset:26624
	ds_read_b128 v[154:157], v248 offset:28672
	ds_read_b128 v[158:161], v248 offset:30720
	ds_read_b128 v[138:141], v247 offset:24576
	ds_read_b128 v[162:165], v249 offset:24576
	ds_read_b128 v[142:145], v247 offset:26624
	ds_read_b128 v[166:169], v249 offset:26624
	ds_read_b128 v[170:173], v249 offset:28672
	ds_read_b128 v[174:177], v249 offset:30720
	s_waitcnt lgkmcnt(10)
	v_mfma_f32_32x32x16_bf16 v[114:129], v[146:149], v[130:133], v[114:129]
	s_waitcnt lgkmcnt(9)
	v_mfma_f32_32x32x16_bf16 v[98:113], v[146:149], v[134:137], v[98:113]
	s_waitcnt lgkmcnt(8)
	v_mfma_f32_32x32x16_bf16 v[82:97], v[150:153], v[130:133], v[82:97]
	v_mfma_f32_32x32x16_bf16 v[66:81], v[150:153], v[134:137], v[66:81]
	s_waitcnt lgkmcnt(7)
	v_mfma_f32_32x32x16_bf16 v[50:65], v[154:157], v[130:133], v[50:65]
	v_mfma_f32_32x32x16_bf16 v[34:49], v[154:157], v[134:137], v[34:49]
	s_waitcnt lgkmcnt(6)
	v_mfma_f32_32x32x16_bf16 v[18:33], v[158:161], v[130:133], v[18:33]
	v_mfma_f32_32x32x16_bf16 v[2:17], v[158:161], v[134:137], v[2:17]
	s_waitcnt lgkmcnt(4)
	v_mfma_f32_32x32x16_bf16 v[114:129], v[162:165], v[138:141], v[114:129]
	s_waitcnt lgkmcnt(3)
	v_mfma_f32_32x32x16_bf16 v[98:113], v[162:165], v[142:145], v[98:113]
	s_waitcnt lgkmcnt(2)
	v_mfma_f32_32x32x16_bf16 v[82:97], v[166:169], v[138:141], v[82:97]
	v_mfma_f32_32x32x16_bf16 v[66:81], v[166:169], v[142:145], v[66:81]
	s_waitcnt lgkmcnt(1)
	v_mfma_f32_32x32x16_bf16 v[50:65], v[170:173], v[138:141], v[50:65]
	v_mfma_f32_32x32x16_bf16 v[34:49], v[170:173], v[142:145], v[34:49]
	s_waitcnt lgkmcnt(0)
	v_mfma_f32_32x32x16_bf16 v[18:33], v[174:177], v[138:141], v[18:33]
	v_mfma_f32_32x32x16_bf16 v[2:17], v[174:177], v[142:145], v[2:17]
	s_barrier
	v_add_u32_e32 v170, s2, v187
	v_or_b32_e32 v168, s3, v204
	v_ashrrev_i32_e32 v172, 11, v170
	v_ashrrev_i32_e32 v173, 6, v168
	v_lshlrev_b32_e32 v174, 12, v172
	v_or_b32_e32 v166, v170, v189
	v_and_b32_e32 v200, 0x7c0, v170
	v_cmp_gt_i32_e32 vcc, 47, v173
	v_ashrrev_i32_e32 v169, 31, v168
	v_ashrrev_i32_e32 v175, 31, v174
	v_ashrrev_i32_e32 v167, 31, v166
	v_lshlrev_b32_e32 v0, 2, v188
	s_and_saveexec_b64 s[54:55], vcc
	s_cbranch_execz .LBB0_370
	v_lshl_add_u64 v[130:131], v[174:175], 2, s[42:43]
	v_lshl_add_u64 v[130:131], v[168:169], 2, v[130:131]
	v_lshl_add_u64 v[132:133], v[166:167], 2, s[40:41]
	v_lshl_add_u64 v[130:131], v[130:131], 0, v[0:1]
	global_load_dword v163, v[132:133], off
	global_load_dword v162, v[132:133], off offset:128
	global_load_dwordx4 v[158:161], v[130:131], off
	global_load_dwordx4 v[154:157], v[130:131], off offset:32
	global_load_dwordx4 v[150:153], v[130:131], off offset:64
	global_load_dwordx4 v[146:149], v[130:131], off offset:96
	global_load_dwordx4 v[142:145], v[130:131], off offset:128
	global_load_dwordx4 v[138:141], v[130:131], off offset:160
	global_load_dwordx4 v[134:137], v[130:131], off offset:192
	s_nop 0
	global_load_dwordx4 v[130:133], v[130:131], off offset:224
	v_cmp_lt_i32_e32 vcc, 7, v173
	s_and_saveexec_b64 s[2:3], vcc
	s_xor_b64 s[60:61], exec, s[2:3]
	s_cbranch_execz .LBB0_356
	s_movk_i32 s2, 0x200
	v_cmp_ne_u32_e32 vcc, s2, v168
	s_and_saveexec_b64 s[2:3], vcc
	s_xor_b64 s[2:3], exec, s[2:3]
	s_cbranch_execz .LBB0_353
	v_cmp_lt_u32_e32 vcc, 17, v173
	s_and_saveexec_b64 s[6:7], vcc
	s_xor_b64 s[62:63], exec, s[6:7]
	s_cbranch_execz .LBB0_350
	v_cmp_lt_u32_e32 vcc, 25, v173
	s_and_saveexec_b64 s[6:7], vcc
	s_xor_b64 s[64:65], exec, s[6:7]
	s_cbranch_execz .LBB0_347
	v_cmp_lt_u32_e32 vcc, 27, v173
	s_and_saveexec_b64 s[6:7], vcc
	s_xor_b64 s[66:67], exec, s[6:7]
	s_cbranch_execz .LBB0_344
	v_cmp_lt_u32_e32 vcc, 29, v173
	s_and_saveexec_b64 s[6:7], vcc
	s_xor_b64 s[68:69], exec, s[6:7]
	s_cbranch_execz .LBB0_341
	v_cmp_lt_u32_e32 vcc, 31, v173
	s_and_saveexec_b64 s[6:7], vcc
	s_xor_b64 s[70:71], exec, s[6:7]
	s_cbranch_execz .LBB0_338
	v_cmp_lt_u32_e32 vcc, 33, v173
	s_and_saveexec_b64 s[6:7], vcc
	s_xor_b64 s[72:73], exec, s[6:7]
	s_cbranch_execz .LBB0_335
	v_cmp_lt_u32_e32 vcc, 35, v173
	s_and_saveexec_b64 s[6:7], vcc
	s_xor_b64 s[58:59], exec, s[6:7]
	s_cbranch_execz .LBB0_332
	v_cmp_lt_u32_e32 vcc, 37, v173
	s_and_saveexec_b64 s[6:7], vcc
	s_xor_b64 s[22:23], exec, s[6:7]
	s_cbranch_execz .LBB0_329
	s_movk_i32 s6, 0xb80
	v_cmp_ne_u32_e32 vcc, s6, v168
	v_mov_b32_e32 v171, 0
	v_mov_b64_e32 v[176:177], 0
	s_mov_b64 s[56:57], 0
	s_and_saveexec_b64 s[74:75], vcc
	s_cbranch_execz .LBB0_328
	v_ashrrev_i32_e32 v171, 31, v170
	v_lshlrev_b64 v[164:165], 10, v[170:171]
	v_lshl_add_u64 v[164:165], s[38:39], 0, v[164:165]
	v_mov_b32_e32 v176, v168
	v_mov_b32_e32 v177, v1
	v_lshl_add_u64 v[164:165], v[176:177], 1, v[164:165]
	s_mov_b64 s[6:7], 0x4ffed00
	s_mov_b64 s[56:57], exec
	v_lshl_add_u64 v[176:177], v[164:165], 0, s[6:7]
	v_mov_b32_e32 v171, 0x200

	.amdhsa_kernel _Z11mega_kernel6Params
		.amdhsa_group_segment_fixed_size 80128
		.amdhsa_private_segment_fixed_size 0
		.amdhsa_kernarg_size 408
		.amdhsa_user_sgpr_count 2
		.amdhsa_user_sgpr_dispatch_ptr 0
		.amdhsa_user_sgpr_queue_ptr 0
		.amdhsa_user_sgpr_kernarg_segment_ptr 1
		.amdhsa_user_sgpr_dispatch_id 0
		.amdhsa_user_sgpr_kernarg_preload_length 0
		.amdhsa_user_sgpr_kernarg_preload_offset 0
		.amdhsa_user_sgpr_private_segment_size 0
		.amdhsa_uses_dynamic_stack 0
		.amdhsa_enable_private_segment 0
		.amdhsa_system_sgpr_workgroup_id_x 1
		.amdhsa_system_sgpr_workgroup_id_y 0
		.amdhsa_system_sgpr_workgroup_id_z 0
		.amdhsa_system_sgpr_workgroup_info 0
		.amdhsa_system_vgpr_workitem_id 2
		.amdhsa_next_free_vgpr 256
		.amdhsa_next_free_sgpr 100
		.amdhsa_accum_offset 256
		.amdhsa_reserve_vcc 1
		.amdhsa_float_round_mode_32 0
		.amdhsa_float_round_mode_16_64 0
		.amdhsa_float_denorm_mode_32 3
		.amdhsa_float_denorm_mode_16_64 3
		.amdhsa_dx10_clamp 1
		.amdhsa_ieee_mode 1
		.amdhsa_fp16_overflow 0
		.amdhsa_tg_split 0
		.amdhsa_exception_fp_ieee_invalid_op 0
		.amdhsa_exception_fp_denorm_src 0
		.amdhsa_exception_fp_ieee_div_zero 0
		.amdhsa_exception_fp_ieee_overflow 0
		.amdhsa_exception_fp_ieee_underflow 0
		.amdhsa_exception_fp_ieee_inexact 0
		.amdhsa_exception_int_div_zero 0
	.end_amdhsa_kernel

amdhsa.kernels:
  - .agpr_count:     0
    .args:
      - .offset:         0
        .size:           152
        .value_kind:     by_value
      - .offset:         152
        .size:           4
        .value_kind:     hidden_block_count_x
      - .offset:         156
        .size:           4
        .value_kind:     hidden_block_count_y
      - .offset:         160
        .size:           4
        .value_kind:     hidden_block_count_z
      - .offset:         164
        .size:           2
        .value_kind:     hidden_group_size_x
      - .offset:         166
        .size:           2
        .value_kind:     hidden_group_size_y
      - .offset:         168
        .size:           2
        .value_kind:     hidden_group_size_z
      - .offset:         170
        .size:           2
        .value_kind:     hidden_remainder_x
      - .offset:         172
        .size:           2
        .value_kind:     hidden_remainder_y
      - .offset:         174
        .size:           2
        .value_kind:     hidden_remainder_z
      - .offset:         192
        .size:           8
        .value_kind:     hidden_global_offset_x
      - .offset:         200
        .size:           8
        .value_kind:     hidden_global_offset_y
      - .offset:         208
        .size:           8
        .value_kind:     hidden_global_offset_z
      - .offset:         216
        .size:           2
        .value_kind:     hidden_grid_dims
      - .offset:         240
        .size:           8
        .value_kind:     hidden_multigrid_sync_arg
    .group_segment_fixed_size: 80128
    .kernarg_segment_align: 8
    .kernarg_segment_size: 408
    .language:       OpenCL C
    .language_version:
      - 2
      - 0
    .max_flat_workgroup_size: 256
    .name:           _Z11mega_kernel6Params
    .private_segment_fixed_size: 0
    .sgpr_count:     106
    .sgpr_spill_count: 92
    .symbol:         _Z11mega_kernel6Params.kd
    .uniform_work_group_size: 1
    .uses_dynamic_stack: false
    .vgpr_count:     256
    .vgpr_spill_count: 0
    .wavefront_size: 64
